# attention: LDS chunk XOR-swizzle removes ds_read_b128 bank conflicts; running max folded into QK MFMA C operand with lazy (threshold 2^8) rescale; exp/add interleaved with PV MFMAs
# speedup vs baseline: 1.0283x; 1.0070x over previous
; __device__ __forceinline__ int ltid() { int t = threadIdx.x; asm volatile("" : "+v"(t)); return t; }
; __device__ __forceinline__ int lsg(int x) { x = __builtin_amdgcn_readfirstlane(x); asm volatile("" : "+s"(x)); return x; }
; __device__ __forceinline__ void phase_attn(KP P, int l_, unsigned char* shm) {
;     const int l = lsg(l_);
;     const int tid = ltid(), wave = tid >> 6, lane = tid & 63, mp = wave >> 2, rq = wave & 3, l15 = lane & 15, g = lane >> 4;
;     const u16* pA = (const u16*)(P->ws + WS_P);
;     u16* OA = (u16*)(P->ws + WS_O);
;     constexpr int KROW = 72, VROW = 136, KT_B = 128 * KROW * 2, VT_B = 128 * VROW * 2, STG = 2 * KT_B + VT_B;
;     const u16* vTg = (const u16*)(P->ws + WS_LO);
;     const float lam_init = 0.8f - 0.6f * __expf(-0.3f * (float)l);
;     float lam;
;     { const float* lq = P->in[11] + (size_t)l * 256; const float s1 = wave_sum(lq[lane] * lq[64 + lane]), s2 = wave_sum(lq[128 + lane] * lq[192 + lane]); lam = __expf(s1) - __expf(s2) + lam_init; }
;     for (int it = blockIdx.x; it < 4096; it += gridDim.x) {
;         const int j = it & 255, pi = 15 - (it >> 8), bh = j >> 1, half = j & 1, b = bh >> 2, h = bh & 3;
;         const int qb = (pi >> 1) * 4 + ((pi & 1) ? (half ? 2 : 3) : (half ? 1 : 0));
;         const int q0 = qb * 64, nt = (qb >> 1) + 1;
;         const size_t tok0 = (size_t)b * SEQ;
;         bf16x8 qf[2];
;         { const u16* qp = pA + (tok0 + q0 + rq * 16 + l15) * 1536 + h * 128 + mp * 64 + g * 8;
;           qf[0] = *(const bf16x8*)qp; qf[1] = *(const bf16x8*)(qp + 32); }
;         f32x4 ot[8];
; #pragma unroll
;         for (int e = 0; e < 8; ++e) ot[e] = (f32x4){0.f, 0.f, 0.f, 0.f};
;         float mrun = -INFINITY, lrun = 0.f;
;         uint4 kreg0, kreg1, kreg2, kreg3, vreg0, vreg1, vreg2, vreg3;
;         const int kc_key = (tid >> 3) & 63, kc_ch = tid & 7, vc_e = tid >> 4, vc_ch = tid & 15;
;         const u16* kgb = pA + (tok0 + kc_key) * 1536 + 512 + h * 128 + kc_ch * 8;
;         const u16* vTb = vTg + ((size_t)bh * 128 + vc_e) * SEQ + vc_ch * 8;
.LBB0_2646:
	s_or_b64 exec, exec, s[4:5]
	v_readlane_b32 s0, v255, 1
	s_mov_b64 s[42:43], s[72:73]
	s_mov_b32 s8, s0
	s_waitcnt lgkmcnt(0)
	v_mov_b32_e32 v0, v228
	s_barrier
	s_load_dwordx2 s[4:5], s[42:43], 0x58
	s_ashr_i32 s9, s8, 31
	s_lshl_b64 s[6:7], s[8:9], 10
	v_and_b32_e32 v2, 63, v0
	v_lshlrev_b32_e32 v1, 2, v2
	s_waitcnt lgkmcnt(0)
	s_add_u32 s6, s4, s6
	s_addc_u32 s7, s5, s7
	global_load_dword v3, v1, s[6:7]
	global_load_dword v4, v1, s[6:7] offset:256
	v_readlane_b32 s0, v254, 6
	v_readlane_b32 s1, v254, 7
	s_and_b64 vcc, exec, s[0:1]
	s_waitcnt vmcnt(0)
	v_mul_f32_e32 v6, v3, v4
	s_nop 1
	v_mov_b32_dpp v6, v6 quad_perm:[1,0,3,2] row_mask:0xf bank_mask:0xf bound_ctrl:1
	v_fmac_f32_e32 v6, v3, v4
	v_mov_b32_e32 v4, v5
	s_nop 0
	v_add_f32_dpp v3, v6, v6 quad_perm:[2,3,0,1] row_mask:0xf bank_mask:0xf bound_ctrl:1
	s_nop 1
	v_add_f32_dpp v3, v3, v3 row_half_mirror row_mask:0xf bank_mask:0xf bound_ctrl:1
	s_nop 1
	v_add_f32_dpp v3, v3, v3 row_mirror row_mask:0xf bank_mask:0xf bound_ctrl:1
	s_nop 1
	v_mov_b32_dpp v4, v3 row_bcast:15 row_mask:0xa bank_mask:0xf
	v_add_f32_e32 v3, v3, v4
	v_mov_b32_e32 v4, v5
	s_nop 1
	v_mov_b32_dpp v4, v3 row_bcast:31 row_mask:0xc bank_mask:0xf
	v_add_f32_e32 v3, v3, v4
	s_nop 0
	v_readlane_b32 s4, v3, 63
	global_load_dword v3, v1, s[6:7] offset:512
	global_load_dword v4, v1, s[6:7] offset:768
	s_waitcnt vmcnt(0)
	v_mul_f32_e32 v6, v3, v4
	s_nop 1
	v_mov_b32_dpp v6, v6 quad_perm:[1,0,3,2] row_mask:0xf bank_mask:0xf bound_ctrl:1
	v_fmac_f32_e32 v6, v3, v4
	v_mov_b32_e32 v4, v5
	s_nop 0
	v_add_f32_dpp v3, v6, v6 quad_perm:[2,3,0,1] row_mask:0xf bank_mask:0xf bound_ctrl:1
	s_nop 1
	v_add_f32_dpp v3, v3, v3 row_half_mirror row_mask:0xf bank_mask:0xf bound_ctrl:1
	s_nop 1
	v_add_f32_dpp v3, v3, v3 row_mirror row_mask:0xf bank_mask:0xf bound_ctrl:1
	s_nop 1
	v_mov_b32_dpp v4, v3 row_bcast:15 row_mask:0xa bank_mask:0xf
	v_add_f32_e32 v3, v3, v4
	v_mov_b32_e32 v4, v5
	s_nop 1
	v_mov_b32_dpp v4, v3 row_bcast:31 row_mask:0xc bank_mask:0xf
	v_add_f32_e32 v3, v3, v4
	s_nop 0
	v_readlane_b32 s5, v3, 63
	s_cbranch_vccz .LBB0_2668
	v_cvt_f32_i32_e32 v3, s8
	v_mov_b32_e32 v6, 0x3fb8aa3b
	v_mul_f32_e32 v4, s4, v6
	v_mul_f32_e32 v6, s5, v6
	v_mul_f32_e32 v3, 0xbe99999a, v3
	v_mul_f32_e32 v3, 0x3fb8aa3b, v3
	v_exp_f32_e32 v3, v3
	v_exp_f32_e32 v4, v4
	v_exp_f32_e32 v6, v6
	v_mov_b32_e32 v7, 0x3f4ccccd
	v_fmamk_f32 v3, v3, 0xbf19999a, v7
	v_lshrrev_b32_e32 v8, 4, v2
	v_sub_f32_e32 v4, v4, v6
	v_add_f32_e32 v165, v3, v4
	v_and_b32_e32 v4, 15, v0
	v_bfe_u32 v10, v0, 6, 2
	v_lshlrev_b32_e32 v164, 2, v8
	v_lshl_or_b32 v194, v10, 4, v4
	v_sub_f32_e32 v197, 1.0, v3
	v_or_b32_e32 v3, 2, v164
	v_cmp_gt_u32_e64 s[12:13], v3, v194
	v_or_b32_e32 v3, 3, v164
	v_cmp_gt_u32_e64 s[14:15], v3, v194
	v_or_b32_e32 v3, 16, v164
	v_cmp_gt_u32_e64 s[16:17], v3, v194
	v_or_b32_e32 v3, 17, v164
	v_cmp_gt_u32_e64 s[18:19], v3, v194
	v_or_b32_e32 v3, 18, v164
	s_load_dwordx2 s[48:49], s[42:43], 0xf8
	v_cmp_gt_u32_e64 s[20:21], v3, v194
	v_or_b32_e32 v3, 19, v164
	v_cmp_gt_u32_e64 s[22:23], v3, v194
	v_or_b32_e32 v3, 32, v164
	v_lshlrev_b32_e32 v6, 3, v0
	v_cmp_gt_u32_e64 s[24:25], v3, v194
	v_or_b32_e32 v3, 33, v164
	v_and_b32_e32 v2, 56, v6
	v_and_b32_e32 v6, 0x78, v6
	v_cmp_gt_u32_e64 s[26:27], v3, v194
	v_or_b32_e32 v3, 34, v164
	v_lshlrev_b32_e32 v160, 1, v6
	v_mov_b32_e32 v161, v5
	v_cmp_gt_u32_e64 s[28:29], v3, v194
	v_or_b32_e32 v3, 35, v164
	v_bfe_u32 v169, v0, 3, 6
	s_waitcnt lgkmcnt(0)
	v_lshl_add_u64 v[6:7], s[48:49], 0, v[160:161]
	s_mov_b64 s[0:1], 0x2bb00000
	v_cmp_gt_u32_e64 s[30:31], v3, v194
	v_or_b32_e32 v3, 48, v164
	v_lshl_add_u64 v[162:163], v[6:7], 0, s[0:1]
	v_mul_u32_u24_e32 v6, 0x48, v169
	v_cmp_gt_u32_e64 s[34:35], v3, v194
	v_or_b32_e32 v3, 49, v164
	s_add_u32 s50, s48, 0x17b00000
	v_ashrrev_i32_e32 v158, 4, v0
	v_lshlrev_b32_e32 v161, 1, v6
	v_lshlrev_b32_e32 v6, 1, v2
	s_movk_i32 s0, 0x88
	v_cmp_gt_u32_e64 s[36:37], v3, v194
	v_or_b32_e32 v3, 50, v164
	s_addc_u32 s51, s49, 0
	v_lshrrev_b32_e32 v9, 6, v0
	v_ashrrev_i32_e32 v11, 8, v0
	v_ashrrev_i32_e32 v159, 31, v158
	v_add3_u32 v190, 0, v161, v6
	v_mul_lo_u32 v6, v158, s0
	v_xor_b32_e32 v195, 64, v1
	v_xor_b32_e32 v196, 0x80, v1
	v_lshl_add_u32 v1, v4, 2, 0
	s_movk_i32 s0, 0x100
	v_cmp_gt_u32_e64 s[38:39], v3, v194
	v_or_b32_e32 v3, 51, v164
	s_add_u32 s60, s48, 0x27b00000
	v_lshlrev_b32_e32 v154, 6, v11
	v_lshlrev_b32_e32 v156, 3, v8
	v_lshlrev_b32_e32 v191, 1, v6
	v_cmp_gt_u32_e64 s[6:7], s0, v0
	v_cmp_gt_u32_e64 s[40:41], v3, v194
	v_lshlrev_b32_e32 v3, 8, v8
	v_lshl_add_u32 v6, v10, 13, v1
	v_lshl_add_u32 v1, v9, 13, v1
	v_lshlrev_b64 v[166:167], 12, v[158:159]
	v_and_b32_e32 v0, 7, v0
	s_addc_u32 s61, s49, 0
	v_ashrrev_i32_e32 v155, 31, v154
	v_add3_u32 v192, 0, v191, v160
	v_mul_i32_i24_e32 v193, 0x4800, v11
	v_cmp_eq_u32_e64 s[4:5], 1, v11
	s_lshl_b64 s[54:55], s[8:9], 9
	v_mul_u32_u24_e32 v198, 0x90, v4
	v_mul_u32_u24_e32 v199, 0x110, v4
	v_cmp_gt_u32_e64 s[8:9], v164, v194
	v_cmp_lt_u32_e64 s[10:11], v164, v194
	v_lshl_or_b32 v166, v4, 4, v166
	v_lshlrev_b32_e32 v168, 4, v0
	v_mov_b32_e32 v157, v5
	v_lshlrev_b32_e32 v170, 1, v156
	v_lshlrev_b32_e32 v172, 1, v2
	v_add_u32_e32 v200, v6, v3
	v_add_u32_e32 v201, v1, v3
	v_bfe_u32 v0, v228, 3, 4
	v_add_u32_e32 v0, 4, v0
	v_bfe_u32 v0, v0, 3, 1
	v_and_b32_e32 v1, 1, v228
	v_lshlrev_b32_e32 v1, 5, v1
	v_sub_u32_e32 v1, 16, v1
	v_mul_i32_i24_e32 v0, v0, v1
	v_add_u32_e32 v161, v161, v0
	v_add_u32_e32 v190, v190, v0
	v_bfe_u32 v0, v228, 4, 4
	v_add_u32_e32 v0, 4, v0
	v_bfe_u32 v0, v0, 3, 1
	v_mul_i32_i24_e32 v0, v0, v1
	v_add_u32_e32 v191, v191, v0
	v_add_u32_e32 v192, v192, v0
	v_and_b32_e32 v0, 15, v228
	v_add_u32_e32 v0, 4, v0
	v_bfe_u32 v0, v0, 3, 1
	v_bfe_u32 v1, v228, 4, 1
	v_lshlrev_b32_e32 v1, 5, v1
	v_sub_u32_e32 v1, 16, v1
	v_mul_i32_i24_e32 v0, v0, v1
	v_add_u32_e32 v198, v198, v0
	v_add_u32_e32 v199, v199, v0
	s_mov_b32 s62, s2
	s_branch .LBB0_2649

; __device__ __forceinline__ void phase_attn(KP P, int l_, unsigned char* shm) {
;     ...
;     for (int it = blockIdx.x; it < 4096; it += gridDim.x) {
;         const int j = it & 255, pi = 15 - (it >> 8), bh = j >> 1, half = j & 1, b = bh >> 2, h = bh & 3;
;         const int qb = (pi >> 1) * 4 + ((pi & 1) ? (half ? 2 : 3) : (half ? 1 : 0));
;         const int q0 = qb * 64, nt = (qb >> 1) + 1;
;         const size_t tok0 = (size_t)b * SEQ;
;         bf16x8 qf[2];
;         { const u16* qp = pA + (tok0 + q0 + rq * 16 + l15) * 1536 + h * 128 + mp * 64 + g * 8;
;           qf[0] = *(const bf16x8*)qp; qf[1] = *(const bf16x8*)(qp + 32); }
;         f32x4 ot[8];
; #pragma unroll
;         for (int e = 0; e < 8; ++e) ot[e] = (f32x4){0.f, 0.f, 0.f, 0.f};
;         float mrun = -INFINITY, lrun = 0.f;
;         uint4 kreg0, kreg1, kreg2, kreg3, vreg0, vreg1, vreg2, vreg3;
;         const int kc_key = (tid >> 3) & 63, kc_ch = tid & 7, vc_e = tid >> 4, vc_ch = tid & 15;
;         const u16* kgb = pA + (tok0 + kc_key) * 1536 + 512 + h * 128 + kc_ch * 8;
;         const u16* vTb = vTg + ((size_t)bh * 128 + vc_e) * SEQ + vc_ch * 8;
;     ...
;         ATT_GLOAD(0); ATT_LSTORE(0); __syncthreads();
.LBB0_2649:
	s_bfe_u32 s0, s62, 0x70001
	s_lshl_b32 s52, s0, 19
	v_lshl_add_u64 v[174:175], v[166:167], 0, s[52:53]
	s_ashr_i32 s52, s62, 8
	s_sub_i32 s52, 15, s52
	s_lshl_b32 s1, s62, 7
	s_and_b32 s56, s62, 1
	s_lshl_b32 s57, s52, 1
	s_and_b32 s1, s1, 0x300
	s_and_b32 s57, s57, 0x7ffffffc
	s_and_b32 s52, s52, 1
	s_xor_b32 s58, s56, 3
	s_cmp_eq_u32 s52, 0
	s_cselect_b32 s52, s56, s58
	s_or_b32 s58, s52, s57
	s_lshl_b32 s56, s62, 8
	s_lshl_b32 s52, s58, 6
	s_and_b32 s59, s56, 0xf800
	s_add_i32 s52, s52, s59
	v_or_b32_e32 v4, s52, v194
	s_lshl_b32 s52, s62, 6
	v_mov_b64_e32 v[0:1], s[50:51]
	s_and_b32 s63, s52, 0x180
	v_mad_u64_u32 v[0:1], s[56:57], v4, s83, v[0:1]
	s_lshl_b32 s52, s63, 1
	s_waitcnt vmcnt(1)
	v_lshl_add_u64 v[18:19], v[0:1], 0, s[52:53]
	v_or_b32_e32 v0, s59, v169
	v_mul_u32_u24_e32 v0, 0x600, v0
	v_lshlrev_b32_e32 v50, 1, v0
	v_mov_b32_e32 v51, v5
	v_lshl_add_u64 v[0:1], s[50:51], 0, v[50:51]
	v_lshl_add_u64 v[0:1], v[0:1], 0, s[52:53]
	v_mov_b32_e32 v173, v5
	s_lshl_b32 s52, s0, 7
	v_lshl_add_u64 v[6:7], v[0:1], 0, v[172:173]
	v_lshl_add_u64 v[0:1], s[52:53], 0, v[158:159]
	s_mov_b32 s0, 0x30000
	v_lshlrev_b64 v[0:1], 12, v[0:1]
	v_add_co_u32_e32 v14, vcc, s0, v6
	v_lshl_add_u64 v[20:21], v[162:163], 0, v[0:1]
	s_nop 0
	v_addc_co_u32_e32 v15, vcc, 0, v7, vcc
	s_mov_b32 s0, 0x20000
	s_waitcnt vmcnt(0)
	v_add_co_u32_e32 v22, vcc, s0, v20
	global_load_dwordx4 v[0:3], v[6:7], off offset:1024
	s_nop 0
	global_load_dwordx4 v[6:9], v[6:7], off offset:1152
	s_nop 0
	global_load_dwordx4 v[10:13], v[14:15], off offset:1024
	global_load_dwordx4 v[26:29], v[20:21], off
	v_addc_co_u32_e32 v23, vcc, 0, v21, vcc
	global_load_dwordx4 v[14:17], v[14:15], off offset:1152
	s_nop 0
	global_load_dwordx4 v[30:33], v[22:23], off
	v_add_co_u32_e32 v22, vcc, s85, v20
	s_mov_b32 s0, 0x60000
	s_nop 0
	v_addc_co_u32_e32 v23, vcc, 0, v21, vcc
	v_add_co_u32_e32 v20, vcc, s0, v20
	v_lshl_add_u64 v[18:19], v[154:155], 1, v[18:19]
	v_mov_b32_e32 v171, v5
	v_addc_co_u32_e32 v21, vcc, 0, v21, vcc
	global_load_dwordx4 v[34:37], v[22:23], off
	global_load_dwordx4 v[38:41], v[20:21], off
	v_lshl_add_u64 v[22:23], v[18:19], 0, v[170:171]
	global_load_dwordx4 v[18:21], v[22:23], off
	s_nop 0
	global_load_dwordx4 v[22:25], v[22:23], off offset:64
	v_mov_b32_e32 v70, v5
	v_mov_b32_e32 v71, v5
	v_mov_b32_e32 v72, v5
	v_mov_b32_e32 v73, v5
	v_mov_b64_e32 v[66:67], v[70:71]
	v_mov_b64_e32 v[62:63], v[70:71]
	v_mov_b64_e32 v[54:55], v[70:71]
	v_mov_b64_e32 v[46:47], v[70:71]
	v_mov_b64_e32 v[42:43], v[70:71]
	s_and_b32 s65, s58, 0x7ffffffe
	v_or3_b32 v176, v168, s1, v50
	v_mov_b64_e32 v[50:51], v[70:71]
	v_mov_b64_e32 v[58:59], v[70:71]
	s_mov_b32 s52, 0
	v_mov_b32_e32 v177, v157
	v_mov_b32_e32 v171, 0
	v_mov_b32_e32 v248, 0
	v_mov_b32_e32 v249, 0
	v_mov_b32_e32 v250, 0
	v_mov_b32_e32 v251, 0
	v_mov_b32_e32 v252, 0xff800000
	v_mov_b32_e32 v253, 0xff800000
	v_mov_b64_e32 v[68:69], v[72:73]
	v_mov_b64_e32 v[64:65], v[72:73]
	v_mov_b64_e32 v[56:57], v[72:73]
	v_mov_b64_e32 v[48:49], v[72:73]
	v_mov_b64_e32 v[44:45], v[72:73]
	s_lshr_b32 s59, s58, 1
	s_add_i32 s64, s58, -1
	s_add_i32 s65, s65, 2
	v_mov_b64_e32 v[52:53], v[72:73]
	v_mov_b64_e32 v[60:61], v[72:73]
	s_mov_b32 s70, 0
	s_waitcnt vmcnt(9)
	ds_write_b128 v190, v[0:3]
	s_waitcnt vmcnt(8)
	ds_write_b128 v190, v[6:9] offset:18432
	s_waitcnt vmcnt(7)
	ds_write_b128 v190, v[10:13] offset:9216
	s_waitcnt vmcnt(5)
	ds_write_b128 v190, v[14:17] offset:27648
	ds_write_b128 v192, v[26:29] offset:36864
	s_waitcnt vmcnt(4)
	ds_write_b128 v192, v[30:33] offset:45568
	s_waitcnt vmcnt(3)
	ds_write_b128 v192, v[34:37] offset:54272
	s_waitcnt vmcnt(2)
	ds_write_b128 v192, v[38:41] offset:62976
	s_waitcnt vmcnt(0) lgkmcnt(0)
	s_barrier
	s_branch .LBB0_2651

; __device__ __forceinline__ float shfl_xor_l(float v, int m, int lane) { return __int_as_float(__builtin_amdgcn_ds_bpermute((lane ^ m) << 2, __float_as_int(v))); }
; __device__ __forceinline__ void phase_attn(KP P, int l_, unsigned char* shm) {
;     ...
;                 const int kb = 2 * t + hf;
;                 if (kb <= qb) {
;                     const u16* Ks = (const u16*)(base + mp * KT_B) + hf * 64 * KROW;
;                     const u16* Vt = (const u16*)(base + 2 * KT_B) + hf * 64;
;                     f32x4 st[4];
;                     bf16x8 kfr[4][2];
; #pragma unroll
;                     for (int kt = 0; kt < 4; ++kt)
; #pragma unroll
;                         for (int ks = 0; ks < 2; ++ks) kfr[kt][ks] = *(const bf16x8*)(Ks + (kt * 16 + l15) * KROW + ks * 32 + g * 8);
;                     uint2 vfa[8][2], vfb[8][2];
; #pragma unroll
;                     for (int e = 0; e < 8; ++e)
; #pragma unroll
;                         for (int k2 = 0; k2 < 2; ++k2) { const u16* vp = Vt + (e * 16 + l15) * VROW + k2 * 32 + g * 4; vfa[e][k2] = *(const uint2*)vp; vfb[e][k2] = *(const uint2*)(vp + 16); }
;                     __builtin_amdgcn_sched_barrier(0);
; #pragma unroll
;                     for (int kt = 0; kt < 4; ++kt) { st[kt] = (f32x4){0.f, 0.f, 0.f, 0.f};
; #pragma unroll
;                         for (int ks = 0; ks < 2; ++ks) st[kt] = __builtin_amdgcn_mfma_f32_16x16x32_bf16(kfr[kt][ks], qf[ks], st[kt], 0, 0, 0); }
;                     if (kb == qb) {
;                         asm volatile("" ::: "memory");
;                         const int qr = rq * 16 + l15;
; #pragma unroll
;                         for (int kt = 0; kt < 4; ++kt)
; #pragma unroll
;                             for (int jj = 0; jj < 4; ++jj) if (kt * 16 + g * 4 + jj > qr) st[kt][jj] = -INFINITY;
;                     }
;                     float mloc = st[0][0];
; #pragma unroll
;                     for (int kt = 0; kt < 4; ++kt)
; #pragma unroll
;                         for (int jj = 0; jj < 4; ++jj) mloc = fmaxf(mloc, st[kt][jj]);
;                     mloc = fmaxf(mloc, shfl_xor_l(mloc, 16, lane)); mloc = fmaxf(mloc, shfl_xor_l(mloc, 32, lane));
.LBB0_2656:
	ds_read_b128 v[138:141], v208
	ds_read_b128 v[142:145], v208 offset:64
	ds_read_b128 v[146:149], v208 offset:2304
	ds_read_b128 v[212:215], v208 offset:2368
	ds_read_b128 v[216:219], v208 offset:4608
	ds_read_b128 v[220:223], v208 offset:4672
	ds_read_b128 v[224:227], v208 offset:6912
	ds_read_b128 v[242:245], v208 offset:6976
	ds_read_b128 v[134:137], v207
	ds_read_b128 v[130:133], v207 offset:64
	ds_read_b128 v[126:129], v206 offset:256
	ds_read_b128 v[122:125], v206 offset:320
	ds_read_b128 v[118:121], v205 offset:512
	ds_read_b128 v[114:117], v205 offset:576
	ds_read_b128 v[110:113], v204 offset:768
	ds_read_b128 v[106:109], v204 offset:832
	ds_read_b128 v[102:105], v203 offset:1024
	ds_read_b128 v[98:101], v203 offset:1088
	ds_read_b128 v[94:97], v202 offset:1280
	ds_read_b128 v[90:93], v202 offset:1344
	ds_read_b128 v[86:89], v173 offset:1536
	ds_read_b128 v[82:85], v173 offset:1600
	v_add_u32_e32 v74, 0x7000, v207
	ds_read_b128 v[78:81], v74 offset:1792
	ds_read_b128 v[74:77], v74 offset:1856
	s_waitcnt lgkmcnt(14)
	v_mfma_f32_16x16x32_bf16 v[138:141], v[138:141], v[18:21], v[248:251]
	s_cmp_lg_u32 s58, s52
	v_mfma_f32_16x16x32_bf16 v[150:153], v[142:145], v[22:25], v[138:141]
	v_mfma_f32_16x16x32_bf16 v[138:141], v[146:149], v[18:21], v[248:251]
	v_mfma_f32_16x16x32_bf16 v[146:149], v[212:215], v[22:25], v[138:141]
	v_mfma_f32_16x16x32_bf16 v[138:141], v[216:219], v[18:21], v[248:251]
	v_mfma_f32_16x16x32_bf16 v[142:145], v[224:227], v[18:21], v[248:251]
	v_mfma_f32_16x16x32_bf16 v[138:141], v[220:223], v[22:25], v[138:141]
	v_mfma_f32_16x16x32_bf16 v[142:145], v[242:245], v[22:25], v[142:145]
	s_cbranch_scc1 .LBB0_2658
	s_nop 0
	v_cndmask_b32_e64 v186, v150, v241, s[8:9]
	v_cndmask_b32_e64 v150, v186, v150, s[10:11]
	v_cndmask_b32_e64 v151, v241, v151, s[10:11]
	v_cndmask_b32_e64 v152, v152, v241, s[12:13]
	v_cndmask_b32_e64 v153, v153, v241, s[14:15]
	v_cndmask_b32_e64 v146, v146, v241, s[16:17]
	v_cndmask_b32_e64 v147, v147, v241, s[18:19]
	v_cndmask_b32_e64 v148, v148, v241, s[20:21]
	v_cndmask_b32_e64 v149, v149, v241, s[22:23]
	v_cndmask_b32_e64 v138, v138, v241, s[24:25]
	v_cndmask_b32_e64 v139, v139, v241, s[26:27]
	v_cndmask_b32_e64 v140, v140, v241, s[28:29]
	v_cndmask_b32_e64 v141, v141, v241, s[30:31]
	v_cndmask_b32_e64 v142, v142, v241, s[34:35]
	v_cndmask_b32_e64 v143, v143, v241, s[36:37]
	v_cndmask_b32_e64 v144, v144, v241, s[38:39]
	v_cndmask_b32_e64 v145, v145, v241, s[40:41]
.LBB0_2658:
	s_nop 2
	v_max3_f32 v186, v150, v151, v152
	v_max3_f32 v187, v153, v146, v147
	v_max3_f32 v186, v186, v148, v149
	v_max_f32_e32 v186, v186, v187
	v_max3_f32 v187, v138, v139, v140
	v_max3_f32 v186, v186, v187, v141
	v_max3_f32 v187, v142, v143, v144
	v_max3_f32 v186, v186, v187, v145
	v_cmp_lt_f32_e32 vcc, v252, v186
	s_and_b64 vcc, exec, vcc
	s_cbranch_scc1 .Lat_rare0
; __device__ __forceinline__ void phase_attn(KP P, int l_, unsigned char* shm) {
;     ...
;                 if (kb <= qb) {
;                     const u16* Ks = (const u16*)(base + mp * KT_B) + hf * 64 * KROW;
;                     const u16* Vt = (const u16*)(base + 2 * KT_B) + hf * 64;
;                     f32x4 st[4];
;                     bf16x8 kfr[4][2];
; #pragma unroll
;                     for (int kt = 0; kt < 4; ++kt)
; #pragma unroll
;                         for (int ks = 0; ks < 2; ++ks) kfr[kt][ks] = *(const bf16x8*)(Ks + (kt * 16 + l15) * KROW + ks * 32 + g * 8);
;                     uint2 vfa[8][2], vfb[8][2];
; #pragma unroll
;                     for (int e = 0; e < 8; ++e)
; #pragma unroll
;                         for (int k2 = 0; k2 < 2; ++k2) { const u16* vp = Vt + (e * 16 + l15) * VROW + k2 * 32 + g * 4; vfa[e][k2] = *(const uint2*)vp; vfb[e][k2] = *(const uint2*)(vp + 16); }
;                     __builtin_amdgcn_sched_barrier(0);
; #pragma unroll
;     ...
;                     const float mnew = fmaxf(mrun, mloc), alpha = __builtin_amdgcn_exp2f(mrun - mnew);
;                     mrun = mnew;
;                     float psum = 0.f;
; #pragma unroll
;                     for (int kt = 0; kt < 4; ++kt)
; #pragma unroll
;                         for (int jj = 0; jj < 4; ++jj) { const float p = __builtin_amdgcn_exp2f(st[kt][jj] - mnew); st[kt][jj] = p; psum += p; }
;                     lrun = lrun * alpha + psum;
; #pragma unroll
;                     for (int e = 0; e < 8; ++e) ot[e] *= alpha;
;                     bf16x8 pb[2];
; #pragma unroll
;                     for (int k2 = 0; k2 < 2; ++k2) { uint4 pk; pk.x = cvt_pk_bf16(st[2 * k2][0], st[2 * k2][1]); pk.y = cvt_pk_bf16(st[2 * k2][2], st[2 * k2][3]);
;                         pk.z = cvt_pk_bf16(st[2 * k2 + 1][0], st[2 * k2 + 1][1]); pk.w = cvt_pk_bf16(st[2 * k2 + 1][2], st[2 * k2 + 1][3]);
;                         pb[k2] = as_bf16x8(pk); }
; #pragma unroll
;                     for (int e = 0; e < 8; ++e)
; #pragma unroll
;                         for (int k2 = 0; k2 < 2; ++k2) { const uint2 v0 = vfa[e][k2], v1 = vfb[e][k2];
;                             uint4 vv; vv.x = v0.x; vv.y = v0.y; vv.z = v1.x; vv.w = v1.y;
;                             ot[e] = __builtin_amdgcn_mfma_f32_16x16x32_bf16(as_bf16x8(vv), pb[k2], ot[e], 0, 0, 0); }
.Lat_comm0:
	v_exp_f32_e32 v150, v150
	v_exp_f32_e32 v151, v151
	v_exp_f32_e32 v152, v152
	v_exp_f32_e32 v153, v153
	v_exp_f32_e32 v146, v146
	v_exp_f32_e32 v147, v147
	v_exp_f32_e32 v148, v148
	v_exp_f32_e32 v149, v149
	v_cvt_pk_bf16_f32 v220, v150, v151
	v_cvt_pk_bf16_f32 v221, v152, v153
	v_cvt_pk_bf16_f32 v222, v146, v147
	v_cvt_pk_bf16_f32 v223, v148, v149
	s_waitcnt lgkmcnt(0)
	s_nop 0
	v_mfma_f32_16x16x32_bf16 v[58:61], v[134:137], v[220:223], v[58:61]
	v_exp_f32_e32 v138, v138
	v_mfma_f32_16x16x32_bf16 v[50:53], v[126:129], v[220:223], v[50:53]
	v_exp_f32_e32 v139, v139
	v_mfma_f32_16x16x32_bf16 v[42:45], v[118:121], v[220:223], v[42:45]
	v_exp_f32_e32 v140, v140
	v_mfma_f32_16x16x32_bf16 v[46:49], v[110:113], v[220:223], v[46:49]
	v_exp_f32_e32 v141, v141
	v_mfma_f32_16x16x32_bf16 v[54:57], v[102:105], v[220:223], v[54:57]
	v_exp_f32_e32 v142, v142
	v_mfma_f32_16x16x32_bf16 v[62:65], v[94:97], v[220:223], v[62:65]
	v_exp_f32_e32 v143, v143
	v_mfma_f32_16x16x32_bf16 v[66:69], v[86:89], v[220:223], v[66:69]
	v_exp_f32_e32 v144, v144
	v_mfma_f32_16x16x32_bf16 v[70:73], v[78:81], v[220:223], v[70:73]
	v_exp_f32_e32 v145, v145
	v_cvt_pk_bf16_f32 v224, v138, v139
	v_cvt_pk_bf16_f32 v225, v140, v141
	v_cvt_pk_bf16_f32 v226, v142, v143
	v_cvt_pk_bf16_f32 v227, v144, v145
	v_add_f32_e32 v187, v150, v151
	v_add_f32_e32 v187, v152, v187
	v_mfma_f32_16x16x32_bf16 v[58:61], v[130:133], v[224:227], v[58:61]
	v_add_f32_e32 v187, v153, v187
	v_add_f32_e32 v187, v146, v187
	v_mfma_f32_16x16x32_bf16 v[50:53], v[122:125], v[224:227], v[50:53]
	v_add_f32_e32 v187, v147, v187
	v_add_f32_e32 v187, v148, v187
	v_mfma_f32_16x16x32_bf16 v[42:45], v[114:117], v[224:227], v[42:45]
	v_add_f32_e32 v187, v149, v187
	v_add_f32_e32 v187, v138, v187
	v_mfma_f32_16x16x32_bf16 v[46:49], v[106:109], v[224:227], v[46:49]
	v_add_f32_e32 v187, v139, v187
	v_add_f32_e32 v187, v140, v187
	v_mfma_f32_16x16x32_bf16 v[54:57], v[98:101], v[224:227], v[54:57]
	v_add_f32_e32 v187, v141, v187
	v_add_f32_e32 v187, v142, v187
	v_mfma_f32_16x16x32_bf16 v[62:65], v[90:93], v[224:227], v[62:65]
	v_add_f32_e32 v187, v143, v187
	v_add_f32_e32 v187, v144, v187
	v_mfma_f32_16x16x32_bf16 v[66:69], v[82:85], v[224:227], v[66:69]
	v_add_f32_e32 v187, v145, v187
	v_mfma_f32_16x16x32_bf16 v[70:73], v[74:77], v[224:227], v[70:73]
	v_add_f32_e32 v171, v171, v187
	s_cmp_ge_u32 s52, s58
	s_cbranch_scc1 .LBB0_2655
.LBB0_2659:
	ds_read_b128 v[138:141], v208 offset:9216
	ds_read_b128 v[142:145], v208 offset:9280
	ds_read_b128 v[146:149], v208 offset:11520
	ds_read_b128 v[212:215], v208 offset:11584
	ds_read_b128 v[216:219], v208 offset:13824
	ds_read_b128 v[220:223], v208 offset:13888
	ds_read_b128 v[224:227], v208 offset:16128
	ds_read_b128 v[242:245], v208 offset:16192
	ds_read_b128 v[134:137], v207 offset:128
	ds_read_b128 v[130:133], v207 offset:192
	ds_read_b128 v[126:129], v206 offset:384
	ds_read_b128 v[122:125], v206 offset:448
	ds_read_b128 v[118:121], v205 offset:640
	ds_read_b128 v[114:117], v205 offset:704
	ds_read_b128 v[110:113], v204 offset:896
	ds_read_b128 v[106:109], v204 offset:960
	ds_read_b128 v[102:105], v203 offset:1152
	ds_read_b128 v[98:101], v203 offset:1216
	ds_read_b128 v[94:97], v202 offset:1408
	ds_read_b128 v[90:93], v202 offset:1472
	ds_read_b128 v[86:89], v173 offset:1664
	ds_read_b128 v[82:85], v173 offset:1728
	v_add_u32_e32 v74, 0x9080, v209
	v_add_u32_e32 v74, 0x7000, v74
	ds_read_b128 v[78:81], v74 offset:1792
	ds_read_b128 v[74:77], v74 offset:1856
	s_waitcnt lgkmcnt(14)
	v_mfma_f32_16x16x32_bf16 v[138:141], v[138:141], v[18:21], v[248:251]
	s_cmp_lg_u32 s64, s52
	v_mfma_f32_16x16x32_bf16 v[150:153], v[142:145], v[22:25], v[138:141]
	v_mfma_f32_16x16x32_bf16 v[138:141], v[146:149], v[18:21], v[248:251]
	v_mfma_f32_16x16x32_bf16 v[146:149], v[212:215], v[22:25], v[138:141]
	v_mfma_f32_16x16x32_bf16 v[138:141], v[216:219], v[18:21], v[248:251]
	v_mfma_f32_16x16x32_bf16 v[142:145], v[224:227], v[18:21], v[248:251]
	v_mfma_f32_16x16x32_bf16 v[138:141], v[220:223], v[22:25], v[138:141]
	v_mfma_f32_16x16x32_bf16 v[142:145], v[242:245], v[22:25], v[142:145]
	s_cbranch_scc1 .LBB0_2661
	s_nop 0
	v_cndmask_b32_e64 v173, v150, v241, s[8:9]
	v_cndmask_b32_e64 v150, v173, v150, s[10:11]
	v_cndmask_b32_e64 v151, v241, v151, s[10:11]
	v_cndmask_b32_e64 v152, v152, v241, s[12:13]
	v_cndmask_b32_e64 v153, v153, v241, s[14:15]
	v_cndmask_b32_e64 v146, v146, v241, s[16:17]
	v_cndmask_b32_e64 v147, v147, v241, s[18:19]
	v_cndmask_b32_e64 v148, v148, v241, s[20:21]
	v_cndmask_b32_e64 v149, v149, v241, s[22:23]
	v_cndmask_b32_e64 v138, v138, v241, s[24:25]
	v_cndmask_b32_e64 v139, v139, v241, s[26:27]
	v_cndmask_b32_e64 v140, v140, v241, s[28:29]
	v_cndmask_b32_e64 v141, v141, v241, s[30:31]
	v_cndmask_b32_e64 v142, v142, v241, s[34:35]
	v_cndmask_b32_e64 v143, v143, v241, s[36:37]
	v_cndmask_b32_e64 v144, v144, v241, s[38:39]
	v_cndmask_b32_e64 v145, v145, v241, s[40:41]

; __device__ __forceinline__ unsigned cvt_pk_bf16(float lo, float hi) { unsigned r; asm volatile("s_nop 0\n\tv_cvt_pk_bf16_f32 %0, %1, %2" : "=v"(r) : "v"(lo), "v"(hi)); return r; }
; __device__ __forceinline__ void phase_attn(KP P, int l_, unsigned char* shm) {
;     ...
;                     const float mnew = fmaxf(mrun, mloc), alpha = __builtin_amdgcn_exp2f(mrun - mnew);
;                     mrun = mnew;
;                     float psum = 0.f;
; #pragma unroll
;                     for (int kt = 0; kt < 4; ++kt)
; #pragma unroll
;                         for (int jj = 0; jj < 4; ++jj) { const float p = __builtin_amdgcn_exp2f(st[kt][jj] - mnew); st[kt][jj] = p; psum += p; }
;                     lrun = lrun * alpha + psum;
; #pragma unroll
;                     for (int e = 0; e < 8; ++e) ot[e] *= alpha;
;                     bf16x8 pb[2];
; #pragma unroll
;                     for (int k2 = 0; k2 < 2; ++k2) { uint4 pk; pk.x = cvt_pk_bf16(st[2 * k2][0], st[2 * k2][1]); pk.y = cvt_pk_bf16(st[2 * k2][2], st[2 * k2][3]);
;                         pk.z = cvt_pk_bf16(st[2 * k2 + 1][0], st[2 * k2 + 1][1]); pk.w = cvt_pk_bf16(st[2 * k2 + 1][2], st[2 * k2 + 1][3]);
;                         pb[k2] = as_bf16x8(pk); }
; #pragma unroll
;                     for (int e = 0; e < 8; ++e)
; #pragma unroll
;                         for (int k2 = 0; k2 < 2; ++k2) { const uint2 v0 = vfa[e][k2], v1 = vfb[e][k2];
;                             uint4 vv; vv.x = v0.x; vv.y = v0.y; vv.z = v1.x; vv.w = v1.y;
;                             ot[e] = __builtin_amdgcn_mfma_f32_16x16x32_bf16(as_bf16x8(vv), pb[k2], ot[e], 0, 0, 0); }
;     ...
;             if (t + 1 < nt) ATT_LSTORE((t + 1) & 1);
;             __syncthreads();
.Lat_comm1:
	v_exp_f32_e32 v150, v150
	v_exp_f32_e32 v151, v151
	v_exp_f32_e32 v152, v152
	v_exp_f32_e32 v153, v153
	v_exp_f32_e32 v146, v146
	v_exp_f32_e32 v147, v147
	v_exp_f32_e32 v148, v148
	v_exp_f32_e32 v149, v149
	v_cvt_pk_bf16_f32 v220, v150, v151
	v_cvt_pk_bf16_f32 v221, v152, v153
	v_cvt_pk_bf16_f32 v222, v146, v147
	v_cvt_pk_bf16_f32 v223, v148, v149
	s_waitcnt lgkmcnt(0)
	s_nop 0
	v_mfma_f32_16x16x32_bf16 v[58:61], v[134:137], v[220:223], v[58:61]
	v_exp_f32_e32 v138, v138
	v_mfma_f32_16x16x32_bf16 v[50:53], v[126:129], v[220:223], v[50:53]
	v_exp_f32_e32 v139, v139
	v_mfma_f32_16x16x32_bf16 v[42:45], v[118:121], v[220:223], v[42:45]
	v_exp_f32_e32 v140, v140
	v_mfma_f32_16x16x32_bf16 v[46:49], v[110:113], v[220:223], v[46:49]
	v_exp_f32_e32 v141, v141
	v_mfma_f32_16x16x32_bf16 v[54:57], v[102:105], v[220:223], v[54:57]
	v_exp_f32_e32 v142, v142
	v_mfma_f32_16x16x32_bf16 v[62:65], v[94:97], v[220:223], v[62:65]
	v_exp_f32_e32 v143, v143
	v_mfma_f32_16x16x32_bf16 v[66:69], v[86:89], v[220:223], v[66:69]
	v_exp_f32_e32 v144, v144
	v_mfma_f32_16x16x32_bf16 v[70:73], v[78:81], v[220:223], v[70:73]
	v_exp_f32_e32 v145, v145
	v_cvt_pk_bf16_f32 v224, v138, v139
	v_cvt_pk_bf16_f32 v225, v140, v141
	v_cvt_pk_bf16_f32 v226, v142, v143
	v_cvt_pk_bf16_f32 v227, v144, v145
	v_add_f32_e32 v187, v150, v151
	v_add_f32_e32 v187, v152, v187
	v_mfma_f32_16x16x32_bf16 v[58:61], v[130:133], v[224:227], v[58:61]
	v_add_f32_e32 v187, v153, v187
	v_add_f32_e32 v187, v146, v187
	v_mfma_f32_16x16x32_bf16 v[50:53], v[122:125], v[224:227], v[50:53]
	v_add_f32_e32 v187, v147, v187
	v_add_f32_e32 v187, v148, v187
	v_mfma_f32_16x16x32_bf16 v[42:45], v[114:117], v[224:227], v[42:45]
	v_add_f32_e32 v187, v149, v187
	v_add_f32_e32 v187, v138, v187
	v_mfma_f32_16x16x32_bf16 v[46:49], v[106:109], v[224:227], v[46:49]
	v_add_f32_e32 v187, v139, v187
	v_add_f32_e32 v187, v140, v187
	v_mfma_f32_16x16x32_bf16 v[54:57], v[98:101], v[224:227], v[54:57]
	v_add_f32_e32 v187, v141, v187
	v_add_f32_e32 v187, v142, v187
	v_mfma_f32_16x16x32_bf16 v[62:65], v[90:93], v[224:227], v[62:65]
	v_add_f32_e32 v187, v143, v187
	v_add_f32_e32 v187, v144, v187
	v_mfma_f32_16x16x32_bf16 v[66:69], v[82:85], v[224:227], v[66:69]
	v_add_f32_e32 v187, v145, v187
	v_mfma_f32_16x16x32_bf16 v[70:73], v[74:77], v[224:227], v[70:73]
	v_add_f32_e32 v171, v171, v187
	s_andn2_b64 vcc, exec, s[56:57]
	s_add_i32 s70, s70, 1
	s_cbranch_vccnz .LBB0_2650

; __device__ __forceinline__ float shfl_xor_l(float v, int m, int lane) { return __int_as_float(__builtin_amdgcn_ds_bpermute((lane ^ m) << 2, __float_as_int(v))); }
; __device__ __forceinline__ void phase_attn(KP P, int l_, unsigned char* shm) {
;     ...
;                     float mloc = st[0][0];
; #pragma unroll
;                     for (int kt = 0; kt < 4; ++kt)
; #pragma unroll
;                         for (int jj = 0; jj < 4; ++jj) mloc = fmaxf(mloc, st[kt][jj]);
;                     mloc = fmaxf(mloc, shfl_xor_l(mloc, 16, lane)); mloc = fmaxf(mloc, shfl_xor_l(mloc, 32, lane));
;                     const float mnew = fmaxf(mrun, mloc), alpha = __builtin_amdgcn_exp2f(mrun - mnew);
;                     mrun = mnew;
;                     float psum = 0.f;
; #pragma unroll
;                     for (int kt = 0; kt < 4; ++kt)
; #pragma unroll
;                         for (int jj = 0; jj < 4; ++jj) { const float p = __builtin_amdgcn_exp2f(st[kt][jj] - mnew); st[kt][jj] = p; psum += p; }
;                     lrun = lrun * alpha + psum;
; #pragma unroll
;                     for (int e = 0; e < 8; ++e) ot[e] *= alpha;
.Lat_rare0:
	v_mov_b32_e32 v187, v186
	s_nop 1
	v_permlane16_swap_b32_e32 v187, v186
	v_max_f32_e32 v186, v186, v187
	v_mov_b32_e32 v187, v186
	s_nop 1
	v_permlane32_swap_b32_e32 v187, v186
	v_max3_f32 v186, v186, v187, v253
	v_sub_f32_e32 v187, 0, v186
	v_min_f32_e32 v187, 0, v187
	v_exp_f32_e32 v246, v187
	v_sub_f32_e32 v150, v150, v186
	v_sub_f32_e32 v151, v151, v186
	v_sub_f32_e32 v152, v152, v186
	v_sub_f32_e32 v153, v153, v186
	v_sub_f32_e32 v146, v146, v186
	v_sub_f32_e32 v147, v147, v186
	v_sub_f32_e32 v148, v148, v186
	v_sub_f32_e32 v149, v149, v186
	v_sub_f32_e32 v138, v138, v186
	v_sub_f32_e32 v139, v139, v186
	v_sub_f32_e32 v140, v140, v186
	v_sub_f32_e32 v141, v141, v186
	v_sub_f32_e32 v142, v142, v186
	v_sub_f32_e32 v143, v143, v186
	v_sub_f32_e32 v144, v144, v186
	v_sub_f32_e32 v145, v145, v186
	v_sub_f32_e32 v248, v248, v186
	v_mov_b32_e32 v252, 0x41000000
	v_mov_b32_e32 v253, 0
	v_mov_b32_e32 v249, v248
	v_mov_b32_e32 v250, v248
	v_mov_b32_e32 v251, v248
	v_mul_f32_e32 v171, v171, v246
	v_pk_mul_f32 v[60:61], v[60:61], v[246:247] op_sel_hi:[1,0]
	v_pk_mul_f32 v[58:59], v[58:59], v[246:247] op_sel_hi:[1,0]
	v_pk_mul_f32 v[52:53], v[52:53], v[246:247] op_sel_hi:[1,0]
	v_pk_mul_f32 v[50:51], v[50:51], v[246:247] op_sel_hi:[1,0]
	v_pk_mul_f32 v[44:45], v[44:45], v[246:247] op_sel_hi:[1,0]
	v_pk_mul_f32 v[42:43], v[42:43], v[246:247] op_sel_hi:[1,0]
	v_pk_mul_f32 v[48:49], v[48:49], v[246:247] op_sel_hi:[1,0]
	v_pk_mul_f32 v[46:47], v[46:47], v[246:247] op_sel_hi:[1,0]
	v_pk_mul_f32 v[56:57], v[56:57], v[246:247] op_sel_hi:[1,0]
	v_pk_mul_f32 v[54:55], v[54:55], v[246:247] op_sel_hi:[1,0]
	v_pk_mul_f32 v[64:65], v[64:65], v[246:247] op_sel_hi:[1,0]
	v_pk_mul_f32 v[62:63], v[62:63], v[246:247] op_sel_hi:[1,0]
	v_pk_mul_f32 v[68:69], v[68:69], v[246:247] op_sel_hi:[1,0]
	v_pk_mul_f32 v[66:67], v[66:67], v[246:247] op_sel_hi:[1,0]
	v_pk_mul_f32 v[72:73], v[72:73], v[246:247] op_sel_hi:[1,0]
	v_pk_mul_f32 v[70:71], v[70:71], v[246:247] op_sel_hi:[1,0]
	s_branch .Lat_comm0
